# v104 + nt (streaming) loads for the z-gate rows in the ssd_s3 epilogue and the V rows of the V^T copy units
# baseline (speedup 1.0000x reference)
; __device__ __forceinline__ void vt_unit(const Params& p, int unit, bfu* tile  ) {
;     const int blk = unit & 15, bh = unit >> 4, h = bh & 15, b = bh >> 4, t0 = blk * 256, tid = threadIdx.x;
;     const bfu* proj = (const bfu*)(p.ws + WS_PROJ);
;     bfu* vt = (bfu*)(p.ws + WS_VT);
; #pragma unroll
;     for (int i = 0; i < 4; ++i) {
;         const int e = tid + 512 * i, t = e >> 3, d8 = (e & 7) * 8;
;         const uint4 v = *(const uint4*)(proj + (size_t)(b * 4096 + t0 + t) * NPROJ + 2048 + h * 64 + d8);
; __device__ __forceinline__ void phase2(const Params& p, unsigned char* lds, int bid, int G) {
;     constexpr int U_CP = 0, U_CS = 32, U_VT = 1024, U_DT = 130, NU = U_CP + U_CS + U_VT + U_DT;
;     const int tid = threadIdx.x;
;     for (int u = bid; u < NU; u += G) {
;         int j = u;
;         if (j < U_VT) { vt_unit(p, j, (bfu*)lds); continue; }
.LBB0_236:
	s_or_b64 exec, exec, s[0:1]
	v_readlane_b32 s0, v252, 1
	v_bfe_u32 v175, v172, 4, 2
	v_readlane_b32 s1, v252, 2
	s_cmpk_gt_i32 s2, 0x4a1
	v_lshrrev_b32_e32 v194, 6, v172
	v_and_b32_e32 v174, 15, v172
	v_lshlrev_b32_e32 v181, 3, v172
	v_lshrrev_b32_e32 v76, 3, v172
	v_lshlrev_b32_e32 v176, 4, v175
	s_waitcnt lgkmcnt(0)
	s_barrier
	s_cbranch_scc1 .LBB0_279
	s_movk_i32 s3, 0xff
	v_cmp_lt_u32_e64 s[10:11], s3, v172
	v_and_b32_e32 v0, 56, v181
	s_movk_i32 s3, 0x214
	v_add_u32_e32 v3, 0x200, v172
	v_or_b32_e32 v4, 0x400, v172
	v_add_u32_e32 v5, 0x600, v172
	v_mad_u32_u24 v1, v0, s3, 0
	v_lshrrev_b32_e32 v100, 3, v3
	v_lshrrev_b32_e32 v102, 3, v4
	v_lshrrev_b32_e32 v104, 3, v5
	v_lshl_add_u32 v99, v76, 1, v1
	v_lshl_add_u32 v101, v100, 1, v1
	v_lshl_add_u32 v103, v102, 1, v1
	v_lshl_add_u32 v105, v104, 1, v1
	v_and_b32_e32 v1, 31, v172
	v_lshlrev_b32_e32 v2, 3, v1
	v_lshl_add_u32 v108, v1, 4, 0
	v_bfe_u32 v1, v172, 3, 2
	v_lshrrev_b32_e32 v109, 5, v3
	v_lshrrev_b32_e32 v111, 5, v4
	v_lshlrev_b32_e32 v3, 1, v1
	v_lshlrev_b32_e32 v4, 3, v0
	v_and_b32_e32 v6, 8, v181
	v_add3_u32 v115, 0, v3, v4
	v_lshlrev_b32_e32 v4, 10, v1
	v_and_b32_e32 v1, 30, v172
	v_lshlrev_b32_e32 v3, 5, v6
	v_add3_u32 v116, 0, v1, v3
	v_lshlrev_b32_e32 v1, 7, v172
	v_and_b32_e32 v8, 0xf00, v1
	v_lshlrev_b32_e32 v1, 14, v194
	v_lshl_add_u32 v1, s2, 17, v1
	v_mov_b32_e32 v65, 0
	v_and_b32_e32 v77, 12, v194
	v_lshrrev_b32_e32 v106, 5, v172
	v_lshrrev_b32_e32 v113, 5, v5
	v_lshlrev_b32_e32 v68, 4, v175
	v_lshl_or_b32 v1, v174, 10, v1
	v_or_b32_e32 v67, 0xffffdf00, v194
	v_and_b32_e32 v66, 0x7f8, v181
	s_mov_b32 s5, 0
	v_cmp_ne_u32_e64 s[6:7], 0, v77
	v_cmp_lt_u32_e64 s[8:9], 4, v77
	v_add_u32_e32 v92, -5, v77
	v_or_b32_e32 v93, 1, v77
	v_add_u32_e32 v94, -4, v77
	v_or_b32_e32 v95, 2, v77
	v_add_u32_e32 v96, -3, v77
	v_or_b32_e32 v97, 3, v194
	v_add_u32_e32 v98, -2, v77
	v_mul_u32_u24_e32 v107, 0x214, v106
	v_mul_u32_u24_e32 v110, 0x214, v109
	v_mul_u32_u24_e32 v112, 0x214, v111
	v_mul_u32_u24_e32 v114, 0x214, v113
	v_lshl_or_b32 v117, v175, 6, v174
	v_mov_b32_e32 v69, v65
	v_add_u32_e32 v70, 0xf7c00000, v1
	s_lshl_b32 s3, s92, 17
	v_lshl_or_b32 v72, v174, 11, v68
	v_mov_b32_e32 v73, v65
	s_movk_i32 s33, 0x410
	v_lshlrev_b32_e32 v118, 2, v174
	s_mov_b32 s41, 0x41a00000
	s_mov_b32 s44, 0x3f2aaaab
	v_mov_b32_e32 v119, 0x3ecc95a3
	s_mov_b32 s45, 0x3f317218
	s_mov_b32 s46, 0x7f800000
	s_mov_b32 s47, 0x33800000
	s_mov_b64 s[14:15], 0x16600000
	s_mov_b64 s[16:17], 0x2000
	s_mov_b64 s[18:19], 0x4000
	s_mov_b64 s[20:21], 0x6000
	s_movk_i32 s48, 0x2000
	s_movk_i32 s49, 0x3000
	s_mov_b64 s[22:23], 0x16800000
	s_mov_b64 s[24:25], 0x9518000
	v_lshlrev_b32_e32 v74, 1, v0
	s_mov_b32 s50, 0x4301000
	v_lshlrev_b32_e32 v78, 1, v2
	s_mov_b64 s[26:27], 0x10600000
	v_lshlrev_b32_e32 v80, 1, v4
	s_mov_b64 s[28:29], 0x12600000
	v_lshlrev_b32_e32 v82, 1, v8
	v_lshlrev_b32_e32 v84, 1, v6
	s_mov_b64 s[30:31], 0x14600000
	v_mov_b32_e32 v86, 0x3f317218
	v_mov_b32_e32 v120, 0x7f800000
	v_mov_b32_e32 v121, 0x7fc00000
	v_mov_b32_e32 v122, 0xff800000
	s_mov_b32 s51, s2
	s_mov_b32 s54, s2
	s_lshl_b32 s55, s54, 8
	s_and_b32 s55, s55, 0xf00
	s_lshl_b32 s56, s54, 4
	s_and_b32 s56, s56, 0xfffff000
	s_or_b32 s55, s56, s55
	s_lshl_b32 s56, s54, 3
	s_and_b32 s56, s56, 0x780
	s_load_dwordx2 s[58:59], s[0:1], 0xb8
	s_waitcnt lgkmcnt(0)
	s_add_u32 s58, s58, s56
	s_addc_u32 s59, s59, 0
	s_add_u32 s58, s58, s50
	s_addc_u32 s59, s59, 0
	v_mov_b32_e32 v158, s58
	v_mov_b32_e32 v159, s59
	v_mov_b32_e32 v160, v74
	v_mov_b32_e32 v161, 0
	v_lshl_add_u64 v[158:159], v[158:159], 0, v[160:161]
	v_or_b32_e32 v160, s55, v76
	v_mad_i64_i32 v[162:163], s[60:61], v160, s49, v[158:159]
	global_load_dwordx4 v[142:145], v[162:163], off nt
	v_or_b32_e32 v160, s55, v100
	v_mad_i64_i32 v[162:163], s[60:61], v160, s49, v[158:159]
	global_load_dwordx4 v[146:149], v[162:163], off nt
	v_or_b32_e32 v160, s55, v102
	v_mad_i64_i32 v[162:163], s[60:61], v160, s49, v[158:159]
	global_load_dwordx4 v[150:153], v[162:163], off nt
	v_add_u32_e32 v160, s55, v104
	v_mad_i64_i32 v[162:163], s[60:61], v160, s49, v[158:159]
	global_load_dwordx4 v[154:157], v[162:163], off nt
	s_branch .LBB0_239

; __device__ __forceinline__ void vt_unit(const Params& p, int unit, bfu* tile  ) {
;     const int blk = unit & 15, bh = unit >> 4, h = bh & 15, b = bh >> 4, t0 = blk * 256, tid = threadIdx.x;
;     const bfu* proj = (const bfu*)(p.ws + WS_PROJ);
;     bfu* vt = (bfu*)(p.ws + WS_VT);
; #pragma unroll
;     for (int i = 0; i < 4; ++i) {
;         const int e = tid + 512 * i, t = e >> 3, d8 = (e & 7) * 8;
;         const uint4 v = *(const uint4*)(proj + (size_t)(b * 4096 + t0 + t) * NPROJ + 2048 + h * 64 + d8);
;         bfu* tp = tile + d8 * 266 + t;
;         tp[0] = (bfu)(v.x & 0xffff); tp[266] = (bfu)(v.x >> 16); tp[2 * 266] = (bfu)(v.y & 0xffff); tp[3 * 266] = (bfu)(v.y >> 16);
;         tp[4 * 266] = (bfu)(v.z & 0xffff); tp[5 * 266] = (bfu)(v.z >> 16); tp[6 * 266] = (bfu)(v.w & 0xffff); tp[7 * 266] = (bfu)(v.w >> 16);
;     }
;     __syncthreads();
; __device__ __forceinline__ void phase2(const Params& p, unsigned char* lds, int bid, int G) {
;     ...
;     for (int u = bid; u < NU; u += G) {
;         int j = u;
;         if (j < U_VT) { vt_unit(p, j, (bfu*)lds); continue; }
.LBB0_278:
	s_load_dwordx2 s[34:35], s[0:1], 0xb8
	s_lshl_b32 s4, s51, 8
	s_and_b32 s36, s4, 0xf00
	s_lshl_b32 s4, s51, 4
	s_and_b32 s4, s4, 0xfffff000
	s_or_b32 s37, s4, s36
	v_or_b32_e32 v0, s37, v76
	s_waitcnt lgkmcnt(0)
	v_mov_b64_e32 v[12:13], s[34:35]
	s_lshl_b32 s4, s51, 3
	v_mad_i64_i32 v[0:1], s[38:39], v0, s49, v[12:13]
	s_and_b32 s4, s4, 0x780
	v_lshl_add_u64 v[0:1], v[0:1], 0, s[4:5]
	v_mov_b32_e32 v75, v65
	v_lshl_add_u64 v[0:1], v[0:1], 0, v[74:75]
	v_add_co_u32_e32 v0, vcc, s50, v0
	v_or_b32_e32 v4, s37, v100
	s_nop 0
	v_addc_co_u32_e32 v1, vcc, 0, v1, vcc
	v_mad_i64_i32 v[4:5], s[38:39], v4, s49, v[12:13]
	v_lshl_add_u64 v[4:5], v[4:5], 0, s[4:5]
	v_lshl_add_u64 v[4:5], v[4:5], 0, v[74:75]
	v_add_co_u32_e32 v4, vcc, s50, v4
	v_or_b32_e32 v8, s37, v102
	s_nop 0
	v_addc_co_u32_e32 v5, vcc, 0, v5, vcc
	v_mad_i64_i32 v[8:9], s[38:39], v8, s49, v[12:13]
	v_lshl_add_u64 v[8:9], v[8:9], 0, s[4:5]
	v_lshl_add_u64 v[8:9], v[8:9], 0, v[74:75]
	v_add_co_u32_e32 v8, vcc, s50, v8
	v_add_u32_e32 v14, s37, v104
	s_nop 0
	v_addc_co_u32_e32 v9, vcc, 0, v9, vcc
	v_mad_i64_i32 v[12:13], s[38:39], v14, s49, v[12:13]
	v_lshl_add_u64 v[12:13], v[12:13], 0, s[4:5]
	v_lshl_add_u64 v[12:13], v[12:13], 0, v[74:75]
	v_add_co_u32_e32 v12, vcc, s50, v12
	s_lshl_b32 s4, s51, 2
	s_nop 0
	v_addc_co_u32_e32 v13, vcc, 0, v13, vcc
	s_waitcnt vmcnt(0)
	v_mov_b64_e32 v[0:1], v[142:143]
	v_mov_b64_e32 v[2:3], v[144:145]
	v_mov_b64_e32 v[4:5], v[146:147]
	v_mov_b64_e32 v[6:7], v[148:149]
	v_mov_b64_e32 v[8:9], v[150:151]
	v_mov_b64_e32 v[10:11], v[152:153]
	v_mov_b64_e32 v[12:13], v[154:155]
	v_mov_b64_e32 v[14:15], v[156:157]
	s_andn2_b32 s4, s4, 63
	s_lshl_b32 s37, s36, 1
	s_add_u32 s38, s34, s37
	v_mov_b32_e32 v79, v65
	s_addc_u32 s39, s35, 0
	v_mov_b32_e32 v81, v65
	v_mov_b32_e32 v83, v65
	v_mov_b32_e32 v85, v65
	s_waitcnt vmcnt(3)
	ds_write_b16 v99, v0
	ds_write_b16_d16_hi v99, v0 offset:532
	ds_write_b16 v99, v1 offset:1064
	ds_write_b16_d16_hi v99, v1 offset:1596
	ds_write_b16 v99, v2 offset:2128
	ds_write_b16_d16_hi v99, v2 offset:2660
	ds_write_b16 v99, v3 offset:3192
	ds_write_b16_d16_hi v99, v3 offset:3724
	s_waitcnt vmcnt(2)
	ds_write_b16 v101, v4
	ds_write_b16_d16_hi v101, v4 offset:532
	ds_write_b16 v101, v5 offset:1064
	ds_write_b16_d16_hi v101, v5 offset:1596
	ds_write_b16 v101, v6 offset:2128
	ds_write_b16_d16_hi v101, v6 offset:2660
	ds_write_b16 v101, v7 offset:3192
	ds_write_b16_d16_hi v101, v7 offset:3724
	s_waitcnt vmcnt(1)
	ds_write_b16 v103, v8
	ds_write_b16_d16_hi v103, v8 offset:532
	ds_write_b16 v103, v9 offset:1064
	ds_write_b16_d16_hi v103, v9 offset:1596
	ds_write_b16 v103, v10 offset:2128
	ds_write_b16_d16_hi v103, v10 offset:2660
	ds_write_b16 v103, v11 offset:3192
	ds_write_b16_d16_hi v103, v11 offset:3724
	s_waitcnt vmcnt(0)
	ds_write_b16 v105, v12
	ds_write_b16_d16_hi v105, v12 offset:532
	ds_write_b16 v105, v13 offset:1064
	ds_write_b16_d16_hi v105, v13 offset:1596
	ds_write_b16 v105, v14 offset:2128
	ds_write_b16_d16_hi v105, v14 offset:2660
	ds_write_b16 v105, v15 offset:3192
	ds_write_b16_d16_hi v105, v15 offset:3724
	v_lshl_add_u64 v[0:1], s[38:39], 0, v[78:79]
	v_add_u32_e32 v2, v108, v107
	s_waitcnt lgkmcnt(0)
	s_barrier
	s_add_i32 s54, s51, s92
	s_cmpk_lt_i32 s54, 0x400
	s_cbranch_scc0 .Lp2_vt_nopf
	s_lshl_b32 s55, s54, 8
	s_and_b32 s55, s55, 0xf00
	s_lshl_b32 s56, s54, 4
	s_and_b32 s56, s56, 0xfffff000
	s_or_b32 s55, s56, s55
	s_lshl_b32 s56, s54, 3
	s_and_b32 s56, s56, 0x780
	s_load_dwordx2 s[58:59], s[0:1], 0xb8
	s_waitcnt lgkmcnt(0)
	s_add_u32 s58, s58, s56
	s_addc_u32 s59, s59, 0
	s_add_u32 s58, s58, s50
	s_addc_u32 s59, s59, 0
	v_mov_b32_e32 v158, s58
	v_mov_b32_e32 v159, s59
	v_mov_b32_e32 v160, v74
	v_mov_b32_e32 v161, 0
	v_lshl_add_u64 v[158:159], v[158:159], 0, v[160:161]
	v_or_b32_e32 v160, s55, v76
	v_mad_i64_i32 v[162:163], s[60:61], v160, s49, v[158:159]
	global_load_dwordx4 v[142:145], v[162:163], off nt
	v_or_b32_e32 v160, s55, v100
	v_mad_i64_i32 v[162:163], s[60:61], v160, s49, v[158:159]
	global_load_dwordx4 v[146:149], v[162:163], off nt
	v_or_b32_e32 v160, s55, v102
	v_mad_i64_i32 v[162:163], s[60:61], v160, s49, v[158:159]
	global_load_dwordx4 v[150:153], v[162:163], off nt
	v_add_u32_e32 v160, s55, v104
	v_mad_i64_i32 v[162:163], s[60:61], v160, s49, v[158:159]
	global_load_dwordx4 v[154:157], v[162:163], off nt

; __device__ __forceinline__ unsigned pk2(float lo, float hi) { f32x2_t v = {lo, hi}; bf16x2_t b = __builtin_convertvector(v, bf16x2_t); return __builtin_bit_cast(unsigned, b); }
; #define MFMA16(a, b, c) __builtin_amdgcn_mfma_f32_16x16x32_bf16((a), (b), (c), 0, 0, 0)
; __device__ __forceinline__ void ssd_s3_unit(const Params& p, int unit, unsigned char* ldsb) {
;     ...
;         for (int ks = 0; ks < 4; ++ks) {
;             const bf16x8 bfr = *(const bf16x8*)(Cs + lrow * 136 + ks * 32 + quad * 8);
; #pragma unroll
;             for (int mt = 0; mt < 4; ++mt) acc[mt] = MFMA16(hf[ks * 4 + mt], bfr, acc[mt]);
;         }
;         const float el = __expf(csl);
; #pragma unroll
;         for (int mt = 0; mt < 4; ++mt) { acc[mt][0] *= el; acc[mt][1] *= el; acc[mt][2] *= el; acc[mt][3] *= el; }
; #pragma unroll
;         for (int kk = 0; kk < 4; ++kk) {
;             if (2 * kk <= wave) {
;                 float mv[8];
; #pragma unroll
;                 for (int j = 0; j < 8; ++j) {
;                     const int tile = 2 * kk + (j >> 2), s = tile * 16 + quad * 4 + (j & 3);
;                     const float cbv = cbt[tile][j & 3];
;                     const float e = __expf(csl - csb[hh * 128 + s]) * dtb[hh * 128 + s];
;                     mv[j] = (s <= lrow) ? cbv * e : 0.f;
;                 }
;                 uint4 pu; pu.x = pk2(mv[0], mv[1]); pu.y = pk2(mv[2], mv[3]); pu.z = pk2(mv[4], mv[5]); pu.w = pk2(mv[6], mv[7]);
;                 const bf16x8 pf = __builtin_bit_cast(bf16x8, pu);
; #pragma unroll
;                 for (int mt = 0; mt < 4; ++mt) {
;                     const bfu* xp = XT + (mt * 16 + l15) * 136 + 32 * kk + quad * 4;
;                     acc[mt] = MFMA16(mk8(*(const uint2*)xp, *(const uint2*)(xp + 16)), pf, acc[mt]);
;                 }
;             }
;         }
;         const float dsk = p.d_skip[h];
;         const size_t row = (size_t)(row0 + lrow);
;         bfu* yg = (bfu*)(p.ws + WS_YG);
; #pragma unroll
;         for (int mt = 0; mt < 4; ++mt) {
;             const int pc = h * 64 + mt * 16 + quad * 4;
;             const uint2 xu = *(const uint2*)(xbc + row * 2048 + pc);
;             const uint2 zu = *(const uint2*)(proj + row * NPROJ + 3072 + pc);
.LBB0_543:
	s_barrier
	v_add_u32_e32 v52, 0, v87
	ds_read_b32 v203, v52
	v_add_u32_e32 v52, v85, v176
	ds_read_b128 v[248:251], v52
	s_andn2_b64 vcc, exec, s[0:1]
	ds_read_b128 v[32:35], v253
	ds_read_b128 v[36:39], v253 offset:4096
	ds_read_b128 v[224:227], v253 offset:8192
	ds_read_b128 v[40:43], v253 offset:12288
	ds_read_b128 v[44:47], v253 offset:13312
	ds_read_b128 v[48:51], v253 offset:1024
	ds_read_b128 v[208:211], v253 offset:5120
	ds_read_b128 v[216:219], v253 offset:9216
	ds_read_b128 v[212:215], v253 offset:6144
	ds_read_b128 v[232:235], v253 offset:10240
	ds_read_b128 v[204:207], v253 offset:2048
	ds_read_b128 v[240:243], v253 offset:14336
	s_waitcnt lgkmcnt(11)
	v_mfma_f32_16x16x32_bf16 v[32:35], v[32:35], v[248:251], 0
	s_waitcnt lgkmcnt(10)
	v_mfma_f32_16x16x32_bf16 v[36:39], v[36:39], v[248:251], 0
	s_waitcnt lgkmcnt(9)
	v_mfma_f32_16x16x32_bf16 v[224:227], v[224:227], v[248:251], 0
	s_waitcnt lgkmcnt(8)
	v_mfma_f32_16x16x32_bf16 v[40:43], v[40:43], v[248:251], 0
	ds_read_b128 v[248:251], v52 offset:64
	ds_read_b128 v[228:231], v253 offset:7168
	ds_read_b128 v[236:239], v253 offset:11264
	ds_read_b128 v[220:223], v253 offset:3072
	ds_read_b128 v[244:247], v253 offset:15360
	s_waitcnt lgkmcnt(4)
	v_mfma_f32_16x16x32_bf16 v[40:43], v[44:47], v[248:251], v[40:43]
	ds_read_b128 v[44:47], v52 offset:128
	s_waitcnt lgkmcnt(12)
	v_mfma_f32_16x16x32_bf16 v[32:35], v[48:51], v[248:251], v[32:35]
	s_waitcnt lgkmcnt(11)
	v_mfma_f32_16x16x32_bf16 v[36:39], v[208:211], v[248:251], v[36:39]
	ds_read_b128 v[208:211], v52 offset:192
	s_waitcnt lgkmcnt(11)
	v_mfma_f32_16x16x32_bf16 v[48:51], v[216:219], v[248:251], v[224:227]
	s_waitcnt lgkmcnt(1)
	v_mfma_f32_16x16x32_bf16 v[36:39], v[212:215], v[44:47], v[36:39]
	s_waitcnt lgkmcnt(9)
	v_mfma_f32_16x16x32_bf16 v[48:51], v[232:235], v[44:47], v[48:51]
	s_waitcnt lgkmcnt(8)
	v_mfma_f32_16x16x32_bf16 v[32:35], v[204:207], v[44:47], v[32:35]
	s_waitcnt lgkmcnt(7)
	v_mfma_f32_16x16x32_bf16 v[204:207], v[240:243], v[44:47], v[40:43]
	s_waitcnt lgkmcnt(0)
	v_mfma_f32_16x16x32_bf16 v[40:43], v[228:231], v[208:211], v[36:39]
	s_waitcnt lgkmcnt(4)
	v_mfma_f32_16x16x32_bf16 v[36:39], v[236:239], v[208:211], v[48:51]
	s_nop 2
	v_mul_f32_e32 v48, 0x3fb8aa3b, v203
	v_add_u32_e32 v50, 0, v89
	v_exp_f32_e32 v52, v48
	v_add_u32_e32 v48, 0x22000, v50
	ds_read_b64 v[48:49], v48
	v_add_u32_e32 v50, 0x22800, v50
	ds_read_b64 v[50:51], v50
	s_waitcnt lgkmcnt(5)
	v_mfma_f32_16x16x32_bf16 v[44:47], v[220:223], v[208:211], v[32:35]
	v_mul_f32_e64 v42, v52, v42
	v_mul_f32_e64 v43, v52, v43
	s_waitcnt lgkmcnt(1)
	v_sub_f32_e32 v48, v203, v48
	v_mul_f32_e32 v48, 0x3fb8aa3b, v48
	v_exp_f32_e32 v48, v48
	v_mfma_f32_16x16x32_bf16 v[32:35], v[244:247], v[208:211], v[204:207]
	s_add_i32 s10, s32, 0x8800
	s_mov_b32 m0, s10
	s_nop 0
	global_load_lds_dwordx4 v[254:255], off nt
	s_add_i32 s10, s10, 0x3c0
	s_mov_b32 m0, s10
	s_nop 0
	global_load_lds_dwordx4 v[254:255], off offset:64 nt
	s_xor_b32 s32, s32, 0x4000
	s_mov_b64 s[98:99], 0x16800000
	s_mov_b64 s[100:101], 0x4301000
	v_lshl_add_u64 v[214:215], s[88:89], 0, v[110:111]
	v_lshl_add_u64 v[216:217], s[88:89], 0, v[102:103]
	v_lshl_add_u64 v[218:219], s[88:89], 0, v[108:109]
	v_lshl_add_u64 v[220:221], s[88:89], 0, v[106:107]
	v_lshl_add_u64 v[222:223], s[88:89], 0, v[104:105]
	v_lshl_add_u64 v[214:215], v[214:215], 0, s[98:99]
	v_lshl_add_u64 v[216:217], v[216:217], 0, s[100:101]
	v_lshl_add_u64 v[218:219], v[218:219], 0, s[100:101]
	v_lshl_add_u64 v[220:221], v[220:221], 0, s[100:101]
	v_lshl_add_u64 v[222:223], v[222:223], 0, s[100:101]
	s_add_u32 s10, s96, s90
	s_addc_u32 s11, s6, s91
	global_load_dwordx2 v[224:225], v[214:215], off
	global_load_dwordx2 v[226:227], v[216:217], off offset:2048 nt
	global_load_dword v240, v53, s[10:11]
	global_load_dwordx2 v[228:229], v[214:215], off offset:32
	global_load_dwordx2 v[230:231], v[218:219], off offset:2048 nt
	global_load_dwordx2 v[232:233], v[214:215], off offset:64
	global_load_dwordx2 v[234:235], v[220:221], off offset:2048 nt
	global_load_dwordx2 v[236:237], v[214:215], off offset:96
	global_load_dwordx2 v[238:239], v[222:223], off offset:2048 nt
	v_mul_f32_e64 v46, v52, v46
	v_mul_f32_e64 v47, v52, v47
	v_pk_mul_f32 v[44:45], v[52:53], v[44:45] op_sel_hi:[0,1]
	s_waitcnt lgkmcnt(0)
	v_mul_f32_e32 v48, v50, v48
	v_mul_f32_e32 v48, v0, v48
	v_cndmask_b32_e64 v208, v48, 0, s[20:21]
	v_sub_f32_e32 v48, v203, v49
	v_mul_f32_e32 v48, 0x3fb8aa3b, v48
	v_exp_f32_e32 v48, v48
	v_add_u32_e32 v49, 0, v91
	v_add_u32_e32 v50, 0x22800, v49
	v_pk_mul_f32 v[40:41], v[52:53], v[40:41] op_sel_hi:[0,1]
	v_mul_f32_e32 v48, v51, v48
	v_mul_f32_e32 v48, v1, v48
	v_cndmask_b32_e64 v209, 0, v48, s[22:23]
	v_add_u32_e32 v48, 0x22000, v49
	v_add_u32_e32 v49, 0, v182
	ds_read_b32 v48, v48
	ds_read_b32 v49, v49
	ds_read_b64 v[50:51], v50
	v_pk_mul_f32 v[38:39], v[52:53], v[38:39] op_sel_hi:[0,1]
	v_pk_mul_f32 v[36:37], v[52:53], v[36:37] op_sel_hi:[0,1]
	s_waitcnt lgkmcnt(2)
	v_sub_f32_e32 v48, v203, v48
	s_waitcnt lgkmcnt(1)
	v_sub_f32_e32 v49, v203, v49
	v_mul_f32_e32 v48, 0x3fb8aa3b, v48
	v_mul_f32_e32 v49, 0x3fb8aa3b, v49
	v_exp_f32_e32 v48, v48
	v_exp_f32_e32 v49, v49
	v_pk_mul_f32 v[34:35], v[52:53], v[34:35] op_sel_hi:[0,1]
	v_pk_mul_f32 v[32:33], v[52:53], v[32:33] op_sel_hi:[0,1]
	s_waitcnt lgkmcnt(0)
	v_pk_mul_f32 v[48:49], v[50:51], v[48:49]
	s_nop 0
	v_pk_mul_f32 v[50:51], v[2:3], v[48:49]
	v_add_u32_e32 v49, 0, v93
	v_add_u32_e32 v48, 0x22000, v49
	v_add_u32_e32 v204, 0x22800, v49
	v_add_u32_e32 v49, 0, v183
	ds_read_b32 v48, v48
	ds_read_b32 v49, v49
	ds_read_b64 v[204:205], v204
	s_waitcnt lgkmcnt(2)
; __device__ __forceinline__ unsigned pk2(float lo, float hi) { f32x2_t v = {lo, hi}; bf16x2_t b = __builtin_convertvector(v, bf16x2_t); return __builtin_bit_cast(unsigned, b); }
; #define MFMA16(a, b, c) __builtin_amdgcn_mfma_f32_16x16x32_bf16((a), (b), (c), 0, 0, 0)
; __device__ __forceinline__ void ssd_s3_unit(const Params& p, int unit, unsigned char* ldsb) {
;     ...
; #pragma unroll
;         for (int kk = 0; kk < 4; ++kk) {
;             if (2 * kk <= wave) {
;                 float mv[8];
; #pragma unroll
;                 for (int j = 0; j < 8; ++j) {
;                     const int tile = 2 * kk + (j >> 2), s = tile * 16 + quad * 4 + (j & 3);
;                     const float cbv = cbt[tile][j & 3];
;                     const float e = __expf(csl - csb[hh * 128 + s]) * dtb[hh * 128 + s];
;                     mv[j] = (s <= lrow) ? cbv * e : 0.f;
;                 }
;                 uint4 pu; pu.x = pk2(mv[0], mv[1]); pu.y = pk2(mv[2], mv[3]); pu.z = pk2(mv[4], mv[5]); pu.w = pk2(mv[6], mv[7]);
;                 const bf16x8 pf = __builtin_bit_cast(bf16x8, pu);
; #pragma unroll
;                 for (int mt = 0; mt < 4; ++mt) {
;                     const bfu* xp = XT + (mt * 16 + l15) * 136 + 32 * kk + quad * 4;
;                     acc[mt] = MFMA16(mk8(*(const uint2*)xp, *(const uint2*)(xp + 16)), pf, acc[mt]);
;                 }
;             }
;         }
	v_sub_f32_e32 v48, v203, v48
	s_waitcnt lgkmcnt(1)
	v_sub_f32_e32 v49, v203, v49
	v_mul_f32_e32 v48, 0x3fb8aa3b, v48
	v_mul_f32_e32 v49, 0x3fb8aa3b, v49
	v_exp_f32_e32 v48, v48
	v_exp_f32_e32 v49, v49
	s_waitcnt lgkmcnt(0)
	v_pk_mul_f32 v[48:49], v[204:205], v[48:49]
	s_nop 0
	v_pk_mul_f32 v[204:205], v[8:9], v[48:49]
	v_add_u32_e32 v49, 0, v95
	v_add_u32_e32 v48, 0x22000, v49
	v_add_u32_e32 v206, 0x22800, v49
	v_add_u32_e32 v49, 0, v184
	ds_read_b32 v48, v48
	ds_read_b32 v49, v49
	ds_read_b64 v[206:207], v206
	s_waitcnt lgkmcnt(2)
	v_sub_f32_e32 v48, v203, v48
	s_waitcnt lgkmcnt(1)
	v_sub_f32_e32 v49, v203, v49
	v_mul_f32_e32 v48, 0x3fb8aa3b, v48
	v_mul_f32_e32 v49, 0x3fb8aa3b, v49
	v_exp_f32_e32 v48, v48
	v_exp_f32_e32 v49, v49
	s_waitcnt lgkmcnt(0)
	v_pk_mul_f32 v[48:49], v[206:207], v[48:49]
	s_nop 0
	v_pk_mul_f32 v[206:207], v[10:11], v[48:49]
	v_cvt_pk_bf16_f32 v49, v50, v51
	v_cndmask_b32_e64 v50, v49, 0, s[26:27]
	v_lshrrev_b32_e32 v49, 16, v49
	v_cndmask_b32_e64 v49, v49, 0, s[24:25]
	v_perm_b32 v49, v49, v50, s33
	v_cvt_pk_bf16_f32 v50, v204, v205
	v_cndmask_b32_e64 v51, v50, 0, s[30:31]
	v_lshrrev_b32_e32 v50, 16, v50
	v_cndmask_b32_e64 v50, v50, 0, s[28:29]
	v_perm_b32 v50, v50, v51, s33
	v_cvt_pk_bf16_f32 v51, v206, v207
	v_cndmask_b32_e64 v204, v51, 0, s[36:37]
	v_lshrrev_b32_e32 v51, 16, v51
	v_cndmask_b32_e64 v51, v51, 0, s[34:35]
	v_perm_b32 v51, v51, v204, s33
	v_add_u32_e32 v204, 0, v200
	v_add_u32_e32 v205, 0x11000, v204
	ds_read_b64 v[206:207], v205
	v_add_u32_e32 v205, 0x11020, v204
	v_cvt_pk_bf16_f32 v48, v208, v209
	ds_read_b64 v[208:209], v205
	v_add_u32_e32 v205, 0, v201
	s_waitcnt lgkmcnt(0)
	v_mfma_f32_16x16x32_bf16 v[44:47], v[206:209], v[48:51], v[44:47]
	v_add_u32_e32 v206, 0x11000, v205
	v_add_u32_e32 v208, 0x11020, v205
	ds_read_b64 v[206:207], v206
	ds_read_b64 v[208:209], v208
	s_waitcnt lgkmcnt(0)
	v_mfma_f32_16x16x32_bf16 v[40:43], v[206:209], v[48:51], v[40:43]
	v_add_u32_e32 v206, 0, v202
	ds_read2_b64 v[208:211], v206 offset1:4
	v_add_u32_e32 v207, 0x1000, v206
	s_waitcnt lgkmcnt(0)
	v_mfma_f32_16x16x32_bf16 v[36:39], v[208:211], v[48:51], v[36:39]
	ds_read2_b64 v[208:211], v207 offset0:32 offset1:36
	s_waitcnt lgkmcnt(0)
	v_mfma_f32_16x16x32_bf16 v[32:35], v[208:211], v[48:51], v[32:35]
	s_cbranch_vccnz .LBB0_546
	v_add_u32_e32 v49, 0, v97
	v_add_u32_e32 v48, 0x22000, v49
	v_add_u32_e32 v50, 0x22800, v49
	v_add_u32_e32 v49, 0, v185
	ds_read_b32 v48, v48
	ds_read_b32 v49, v49
	ds_read_b64 v[50:51], v50
	s_waitcnt lgkmcnt(2)
	v_sub_f32_e32 v48, v203, v48
	s_waitcnt lgkmcnt(1)
	v_sub_f32_e32 v49, v203, v49
	v_mul_f32_e32 v48, 0x3fb8aa3b, v48
	v_mul_f32_e32 v49, 0x3fb8aa3b, v49
	v_exp_f32_e32 v48, v48
	v_exp_f32_e32 v49, v49
	s_waitcnt lgkmcnt(0)
	v_pk_mul_f32 v[48:49], v[50:51], v[48:49]
	v_add_u32_e32 v51, 0, v163
	v_add_u32_e32 v50, 0x22000, v51
	v_add_u32_e32 v52, 0x22800, v51
	v_add_u32_e32 v51, 0, v186
	ds_read_b32 v50, v50
	ds_read_b32 v51, v51
	ds_read_b64 v[208:209], v52
	v_add_u32_e32 v52, 0, v164
	v_pk_mul_f32 v[48:49], v[12:13], v[48:49]
	s_waitcnt lgkmcnt(2)
	v_sub_f32_e32 v50, v203, v50
	s_waitcnt lgkmcnt(1)
	v_sub_f32_e32 v51, v203, v51
	v_mul_f32_e32 v50, 0x3fb8aa3b, v50
	v_mul_f32_e32 v51, 0x3fb8aa3b, v51
	v_exp_f32_e32 v50, v50
	v_exp_f32_e32 v51, v51
	v_cvt_pk_bf16_f32 v48, v48, v49
	v_cndmask_b32_e64 v49, v48, 0, s[40:41]
	v_lshrrev_b32_e32 v48, 16, v48
	s_waitcnt lgkmcnt(0)
	v_pk_mul_f32 v[50:51], v[208:209], v[50:51]
	v_add_u32_e32 v208, 0x22000, v52
	v_add_u32_e32 v209, 0, v187
	ds_read_b32 v208, v208
	ds_read_b32 v209, v209
	v_add_u32_e32 v52, 0x22800, v52
	ds_read_b64 v[210:211], v52
	v_add_u32_e32 v52, 0, v165
	s_waitcnt lgkmcnt(2)
	v_sub_f32_e32 v208, v203, v208
	s_waitcnt lgkmcnt(1)
	v_sub_f32_e32 v209, v203, v209
	v_mul_f32_e32 v208, 0x3fb8aa3b, v208
	v_mul_f32_e32 v209, 0x3fb8aa3b, v209
	v_exp_f32_e32 v208, v208
	v_exp_f32_e32 v209, v209
	v_pk_mul_f32 v[50:51], v[14:15], v[50:51]
	v_cndmask_b32_e64 v48, v48, 0, s[38:39]
	v_perm_b32 v48, v48, v49, s33
	s_waitcnt lgkmcnt(0)
	v_pk_mul_f32 v[208:209], v[210:211], v[208:209]
	v_add_u32_e32 v210, 0x22000, v52
	v_add_u32_e32 v211, 0, v188
	ds_read_b32 v210, v210
	ds_read_b32 v211, v211
	v_add_u32_e32 v52, 0x22800, v52
	ds_read_b64 v[212:213], v52
	v_cvt_pk_bf16_f32 v49, v50, v51
	s_waitcnt lgkmcnt(2)
	v_sub_f32_e32 v210, v203, v210
	s_waitcnt lgkmcnt(1)
	v_sub_f32_e32 v211, v203, v211
	v_mul_f32_e32 v210, 0x3fb8aa3b, v210
	v_mul_f32_e32 v211, 0x3fb8aa3b, v211
	v_exp_f32_e32 v210, v210
	v_exp_f32_e32 v211, v211
	v_cndmask_b32_e64 v50, v49, 0, s[44:45]
	v_lshrrev_b32_e32 v49, 16, v49
	v_pk_mul_f32 v[208:209], v[4:5], v[208:209]
	v_cndmask_b32_e64 v49, v49, 0, s[42:43]
	v_perm_b32 v49, v49, v50, s33
	v_cvt_pk_bf16_f32 v50, v208, v209
	s_waitcnt lgkmcnt(0)
	v_pk_mul_f32 v[210:211], v[212:213], v[210:211]
	v_cndmask_b32_e64 v51, v50, 0, s[48:49]
	v_lshrrev_b32_e32 v50, 16, v50
	v_pk_mul_f32 v[210:211], v[6:7], v[210:211]
	v_cndmask_b32_e64 v50, v50, 0, s[46:47]
	v_perm_b32 v50, v50, v51, s33
	v_cvt_pk_bf16_f32 v51, v210, v211
	v_cndmask_b32_e64 v52, v51, 0, s[52:53]
	v_lshrrev_b32_e32 v51, 16, v51
	v_cndmask_b32_e64 v51, v51, 0, s[50:51]
	v_perm_b32 v51, v51, v52, s33
	v_add_u32_e32 v52, 0x11040, v204
	ds_read_b64 v[208:209], v52
	v_add_u32_e32 v52, 0x11060, v204
	ds_read_b64 v[210:211], v52
	v_add_u32_e32 v52, 0x11040, v205
	s_waitcnt lgkmcnt(0)
	v_mfma_f32_16x16x32_bf16 v[44:47], v[208:211], v[48:51], v[44:47]
	ds_read_b64 v[208:209], v52
	v_add_u32_e32 v52, 0x11060, v205
	ds_read_b64 v[210:211], v52
	s_waitcnt lgkmcnt(0)
	v_mfma_f32_16x16x32_bf16 v[40:43], v[208:211], v[48:51], v[40:43]
	ds_read2_b64 v[208:211], v206 offset0:8 offset1:12
	s_waitcnt lgkmcnt(0)
	v_mfma_f32_16x16x32_bf16 v[36:39], v[208:211], v[48:51], v[36:39]
	ds_read2_b64 v[208:211], v207 offset0:40 offset1:44
	s_waitcnt lgkmcnt(0)
	v_mfma_f32_16x16x32_bf16 v[32:35], v[208:211], v[48:51], v[32:35]
	s_andn2_b64 vcc, exec, s[94:95]
	s_cbranch_vccz .LBB0_547
